# U3: as U2, plus the compiler-inserted vmcnt(0) store drain in the GU tile-loop header removed (hand-counted K-loop waits only get stronger)
# baseline (speedup 1.0000x reference)
; template <class Epi, class Sched, bool ALIGN_EPI = false, bool SP2 = false>
; __device__ __forceinline__ void gemm_phase(PG8_LAS unsigned char* lds, const Gemm g, const Sched& S, const Epi& E) {
;     ...
; #pragma unroll
;         for (int a = 0; a < 2; ++a)
; #pragma unroll
;             for (int b = 0; b < 2; ++b)
; #pragma unroll
;                 for (int m = 0; m < 4; ++m)
; #pragma unroll
;                     for (int n = 0; n < 2; ++n) acc[a][b][m][n] = (f32x4){0.f, 0.f, 0.f, 0.f};
;     __device__ __forceinline__ void operator()(const f32x4 (&acc)[2][2][4][2], const Unit& u, int wr, int wc, int fr, int fq) const {
;         const int row0 = u.pm * 256 + wr * 64 + fr, col0 = u.pn * 128 + wc * 32 + fq * 8;
;         float sv[2][4];
; #pragma unroll
;         for (int ai = 0; ai < 2; ++ai)
; #pragma unroll
;             for (int m = 0; m < 4; ++m) sv[ai][m] = rs[row0 + ai * 128 + m * 16];
.LBB0_724:
	s_ashr_i32 s11, s10, 31
	s_lshl_b64 s[12:13], s[10:11], 20
	v_readlane_b32 s14, v251, 8
	v_readlane_b32 s15, v251, 9
	s_add_u32 s12, s14, s12
	s_addc_u32 s13, s15, s13
	s_and_b64 s[14:15], s[6:7], exec
	s_cselect_b32 s11, s13, s19
	s_cselect_b32 s33, s12, s18
	s_ashr_i32 s9, s8, 31
	s_lshl_b64 s[14:15], s[8:9], 20
	s_add_u32 s14, s26, s14
	s_addc_u32 s15, s27, s15
	s_and_b64 s[22:23], s[6:7], exec
	s_cselect_b32 s9, s15, s21
	s_cselect_b32 s38, s14, s20
	s_add_u32 s18, s18, 0x80080
	s_addc_u32 s19, s19, 0
	s_add_u32 s39, s20, 0x100
	v_mov_b32_e32 v0, 0
	s_addc_u32 s40, s21, 0
	s_mov_b32 s41, -2
	v_mov_b32_e32 v1, v0
	v_mov_b32_e32 v2, v0
	v_mov_b32_e32 v3, v0
	v_mov_b32_e32 v8, v0
	v_mov_b32_e32 v9, v0
	v_mov_b32_e32 v10, v0
	v_mov_b32_e32 v11, v0
	v_mov_b32_e32 v16, v0
	v_mov_b32_e32 v17, v0
	v_mov_b32_e32 v18, v0
	v_mov_b32_e32 v19, v0
	v_mov_b32_e32 v24, v0
	v_mov_b32_e32 v25, v0
	v_mov_b32_e32 v26, v0
	v_mov_b32_e32 v27, v0
	v_mov_b32_e32 v32, v0
	v_mov_b32_e32 v33, v0
	v_mov_b32_e32 v34, v0
	v_mov_b32_e32 v35, v0
	v_mov_b32_e32 v40, v0
	v_mov_b32_e32 v41, v0
	v_mov_b32_e32 v42, v0
	v_mov_b32_e32 v43, v0
	v_mov_b32_e32 v48, v0
	v_mov_b32_e32 v49, v0
	v_mov_b32_e32 v50, v0
	v_mov_b32_e32 v51, v0
	v_mov_b32_e32 v56, v0
	v_mov_b32_e32 v57, v0
	v_mov_b32_e32 v58, v0
	v_mov_b32_e32 v59, v0
	v_mov_b32_e32 v4, v0
	v_mov_b32_e32 v5, v0
	v_mov_b32_e32 v6, v0
	v_mov_b32_e32 v7, v0
	v_mov_b32_e32 v12, v0
	v_mov_b32_e32 v13, v0
	v_mov_b32_e32 v14, v0
	v_mov_b32_e32 v15, v0
	v_mov_b32_e32 v20, v0
	v_mov_b32_e32 v21, v0
	v_mov_b32_e32 v22, v0
	v_mov_b32_e32 v23, v0
	v_mov_b32_e32 v28, v0
	v_mov_b32_e32 v29, v0
	v_mov_b32_e32 v30, v0
	v_mov_b32_e32 v31, v0
	v_mov_b32_e32 v36, v0
	v_mov_b32_e32 v37, v0
	v_mov_b32_e32 v38, v0
	v_mov_b32_e32 v39, v0
	v_mov_b32_e32 v44, v0
	v_mov_b32_e32 v45, v0
	v_mov_b32_e32 v46, v0
	v_mov_b32_e32 v47, v0
	v_mov_b32_e32 v52, v0
	v_mov_b32_e32 v53, v0
	v_mov_b32_e32 v54, v0
	v_mov_b32_e32 v55, v0
	v_mov_b32_e32 v60, v0
	v_mov_b32_e32 v61, v0
	v_mov_b32_e32 v62, v0
	v_mov_b32_e32 v63, v0
	v_mov_b32_e32 v64, v0
	v_mov_b32_e32 v65, v0
	v_mov_b32_e32 v66, v0
	v_mov_b32_e32 v67, v0
	v_mov_b32_e32 v72, v0
	v_mov_b32_e32 v73, v0
	v_mov_b32_e32 v74, v0
	v_mov_b32_e32 v75, v0
	v_mov_b32_e32 v80, v0
	v_mov_b32_e32 v81, v0
	v_mov_b32_e32 v82, v0
	v_mov_b32_e32 v83, v0
	v_mov_b32_e32 v88, v0
	v_mov_b32_e32 v89, v0
	v_mov_b32_e32 v90, v0
	v_mov_b32_e32 v91, v0
	v_mov_b32_e32 v96, v0
	v_mov_b32_e32 v97, v0
	v_mov_b32_e32 v98, v0
	v_mov_b32_e32 v99, v0
	v_mov_b32_e32 v104, v0
	v_mov_b32_e32 v105, v0
	v_mov_b32_e32 v106, v0
	v_mov_b32_e32 v107, v0
	v_mov_b32_e32 v116, v0
	v_mov_b32_e32 v117, v0
	v_mov_b32_e32 v118, v0
	v_mov_b32_e32 v119, v0
	v_mov_b32_e32 v120, v0
	v_mov_b32_e32 v121, v0
	v_mov_b32_e32 v122, v0
	v_mov_b32_e32 v123, v0
	v_mov_b32_e32 v68, v0
	v_mov_b32_e32 v69, v0
	v_mov_b32_e32 v70, v0
	v_mov_b32_e32 v71, v0
	v_mov_b32_e32 v76, v0
	v_mov_b32_e32 v77, v0
	v_mov_b32_e32 v78, v0
	v_mov_b32_e32 v79, v0
	v_mov_b32_e32 v84, v0
	v_mov_b32_e32 v85, v0
	v_mov_b32_e32 v86, v0
	v_mov_b32_e32 v87, v0
	v_mov_b32_e32 v92, v0
	v_mov_b32_e32 v93, v0
	v_mov_b32_e32 v94, v0
	v_mov_b32_e32 v95, v0
	v_mov_b32_e32 v100, v0
	v_mov_b32_e32 v101, v0
	v_mov_b32_e32 v102, v0
	v_mov_b32_e32 v103, v0
	v_mov_b32_e32 v108, v0
	v_mov_b32_e32 v109, v0
	v_mov_b32_e32 v110, v0
	v_mov_b32_e32 v111, v0
	v_mov_b32_e32 v112, v0
	v_mov_b32_e32 v113, v0
	v_mov_b32_e32 v114, v0
	v_mov_b32_e32 v115, v0
	v_mov_b32_e32 v124, v0
	v_mov_b32_e32 v125, v0
	v_mov_b32_e32 v126, v0
	v_mov_b32_e32 v127, v0
	v_readlane_b32 s100, v251, 10
	v_readlane_b32 s101, v251, 11
	v_lshl_add_u32 v245, s16, 8, v147
	v_lshlrev_b32_e32 v245, 2, v245
	s_nop 3
	global_load_dword v142, v245, s[100:101]
	global_load_dword v190, v245, s[100:101] offset:64
	global_load_dword v244, v245, s[100:101] offset:128
	global_load_dword v186, v245, s[100:101] offset:192
	global_load_dword v152, v245, s[100:101] offset:512
	global_load_dword v150, v245, s[100:101] offset:576
	global_load_dword v148, v245, s[100:101] offset:640
	global_load_dword v188, v245, s[100:101] offset:704
	s_mov_b64 s[50:51], 0x80
